# P13->P14 grid barrier replaced by a 4-workgroup row-panel counter sync (same XCD/L2, no L2 writeback needed) on top of best
# speedup vs baseline: 1.0095x; 1.0095x over previous
.LBB0_1638:
	s_waitcnt vmcnt(0)
	s_waitcnt lgkmcnt(0)
	s_barrier
	s_and_saveexec_b64 s[8:9], s[92:93]
	s_cbranch_execz .LBB0_1690
	s_and_b32 s0, s2, 7
	s_lshl_b32 s0, s0, 3
	s_lshr_b32 s1, s2, 5
	s_add_i32 s0, s0, s1
	s_lshl_b32 s0, s0, 8
	s_add_i32 s0, s0, 0x2b5d004
	v_mov_b32_e32 v2, s0
	v_mov_b32_e32 v3, 1
	global_atomic_add v2, v3, s[88:89]
	s_mov_b32 s1, 0x100000
.Lpsync13_poll:
	global_load_dword v3, v2, s[88:89] sc1
	s_waitcnt vmcnt(0)
	v_cmp_lt_u32_e32 vcc, 3, v3
	s_cbranch_vccnz .Lpsync13_done
	s_sleep 1
	s_sub_u32 s1, s1, 1
	s_cmp_lg_u32 s1, 0
	s_cbranch_scc1 .Lpsync13_poll
.Lpsync13_done:
	buffer_inv sc1
	s_waitcnt vmcnt(0)
.LBB0_1690:
	s_or_b64 exec, exec, s[8:9]
	s_waitcnt lgkmcnt(0)
	v_mov_b32_e32 v2, v0
	s_barrier
	s_load_dwordx4 s[12:15], s[96:97], 0xe0
	v_readlane_b32 s0, v254, 5
	v_mov_b32_e32 v6, v0
	v_readlane_b32 s1, v254, 6
	s_waitcnt lgkmcnt(0)
	s_add_u32 s3, s14, 0xae00000
	s_addc_u32 s4, s15, 0
	s_and_b64 vcc, exec, s[0:1]
	v_readfirstlane_b32 s0, v6
	s_cbranch_vccnz .LBB0_1692
	s_and_b32 s1, s83, 56
	s_ashr_i32 s5, s2, 5
	s_add_i32 s6, s1, s5
	s_ashr_i32 s7, s6, 31
	s_lshl_b64 s[8:9], s[6:7], 19
	s_add_u32 s60, s3, s8
	s_addc_u32 s61, s4, s9
	s_lshl_b32 s1, s2, 5
	s_and_b32 s83, s1, 0x300
	s_lshl_b32 s1, s83, 11
	s_add_u32 s1, s14, s1
	s_addc_u32 s5, s15, 0
	s_add_u32 s62, s1, 0xc00000
	s_addc_u32 s63, s5, 0
	s_lshl_b32 s1, s83, 2
	s_add_u32 s1, s14, s1
	s_addc_u32 s5, s15, 0
	s_add_u32 s56, s1, 0x2106000
	s_addc_u32 s57, s5, 0
	s_lshl_b32 s84, s6, 8
	s_branch .LBB0_1693
